# thin kv tile: MFMA-computing waves run at raised wave priority (s_setprio 2) for the duration of the tile
# speedup vs baseline: 1.0033x; 1.0033x over previous
; template <bool SWAP, class Epi, bool THIN = false> ...
;     ...
;     unsigned ap[4], bp[4];
; #pragma unroll
;     for (int i = 0; i < 4; ++i) {
;       const int r = (tid >> 3) + 64 * i;
;       const int cs = tid & 7;
;       const int c = ((cs ^ ((r >> 1) & 7)) << 3);
;       const int sub = 2 * mt + (r >> 7);
;       const int g = sub / tpg, ti = sub - g * tpg;
;       int rig = ti * step - halo + (r & 127); rig = rig < 0 ? 0 : (rig > grows - 1 ? grows - 1 : rig);
;       ap[i] = (unsigned)((g * a_gstride + a_goff + rig) * lda + c);
;       int br = nt * 256 + r; br = br > N - 1 ? N - 1 : br;
;       bp[i] = (unsigned)(br * K + c);
;     }
;     const bool have_next = false;
;     f32x4 acc[4][8];
; #pragma unroll
;     for (int m = 0; m < 4; ++m)
; #pragma unroll
;       for (int n = 0; n < 8; ++n) acc[m][n] = (f32x4){0.f, 0.f, 0.f, 0.f};
;     if (!pre_issued) {
; #pragma unroll
;       for (int i = 0; i < 4; ++i) { GLDS16(A + (size_t)ap[i], smem + tid * 16 + i * 8192); GLDS16(Bt + (size_t)bp[i], smem + 32768 + tid * 16 + i * 8192); }
;     }
;     pre_issued = have_next;
;     for (int st = 0; st < ns; ++st) {
;       asm volatile("s_waitcnt vmcnt(0)" ::: "memory");
;       __builtin_amdgcn_s_barrier();
;       asm volatile("" ::: "memory");
;       if (st + 1 < ns) {
;         char* nb = smem + ((st + 1) & 1) * 65536;
;         const int ko = (st + 1) * 64;
; #pragma unroll
;         for (int i = 0; i < 4; ++i) { GLDS16(A + (size_t)(ap[i] + ko), nb + tid * 16 + i * 8192); GLDS16(Bt + (size_t)(bp[i] + ko), nb + 32768 + tid * 16 + i * 8192); }
;       }
;       const char* sa = smem + (st & 1) * 65536 + (wr * 64 + fr) * 128;
;       const char* sb = smem + (st & 1) * 65536 + 32768 + (wc * 128 + fr) * 128;
;       if constexpr (THIN) {
;         if (wc == 0) {
; #pragma unroll
;           for (int ks = 0; ks < 2; ++ks) {
;             bf16x8 af[4], bf[2];
; #pragma unroll
;             for (int m = 0; m < 4; ++m) af[m] = *(const bf16x8*)(sa + m * 2048 + (((ks * 4 + fq) ^ swz) << 4));
; #pragma unroll
;             for (int n = 0; n < 2; ++n) bf[n] = *(const bf16x8*)(sb + n * 2048 + (((ks * 4 + fq) ^ swz) << 4));
; #pragma unroll
;             for (int m = 0; m < 4; ++m)
; #pragma unroll
;               for (int n = 0; n < 2; ++n)
;                 acc[m][n] = SWAP ? __builtin_amdgcn_mfma_f32_16x16x32_bf16(bf[n], af[m], acc[m][n], 0, 0, 0)
.LBB0_1525:
	s_ashr_i32 s7, s3, 31
	s_lshr_b32 s7, s7, 29
	s_add_i32 s6, s3, 0x108
	s_add_i32 s7, s3, s7
	s_and_b32 s7, s7, -8
	s_and_b32 s6, s6, 7
	s_or_b32 s6, s7, s6
	s_lshl_b32 s9, s6, 1
	v_add_u32_e32 v2, s9, v57
	v_mul_hi_i32 v4, v2, s33
	v_lshrrev_b32_e32 v5, 31, v4
	v_ashrrev_i32_e32 v4, 2, v4
	v_add_u32_e32 v6, v4, v5
	s_sub_i32 s8, s3, s7
	v_mad_u64_u32 v[4:5], s[6:7], v6, s74, v[2:3]
	v_lshl_or_b32 v2, v4, 7, v58
	v_min_i32_e32 v2, 0x8ff, v2
	v_cmp_lt_i32_e32 vcc, -1, v4
	s_ashr_i32 s46, s8, 3
	s_lshl_b32 s8, s46, 8
	v_cndmask_b32_e32 v2, 0, v2, vcc
	v_mad_u64_u32 v[4:5], s[6:7], v6, s75, v[2:3]
	v_lshl_or_b32 v2, v4, 10, v55
	v_add_u32_e32 v4, s8, v54
	v_min_i32_e32 v4, 31, v4
	v_lshl_or_b32 v38, v4, 10, v55
	v_add_u32_e32 v4, s9, v60
	v_mul_hi_i32 v5, v4, s33
	v_lshrrev_b32_e32 v6, 31, v5
	v_ashrrev_i32_e32 v5, 2, v5
	v_add_u32_e32 v6, v5, v6
	v_mad_u64_u32 v[4:5], s[6:7], v6, s74, v[4:5]
	v_lshl_or_b32 v5, v4, 7, v61
	v_min_i32_e32 v5, 0x8ff, v5
	v_cmp_lt_i32_e32 vcc, -1, v4
	v_add_u32_e32 v8, s9, v65
	v_lshl_add_u64 v[46:47], v[2:3], 1, s[36:37]
	v_cndmask_b32_e32 v4, 0, v5, vcc
	v_mad_u64_u32 v[4:5], s[6:7], v6, s75, v[4:5]
	v_add_u32_e32 v5, s8, v59
	v_min_i32_e32 v5, 31, v5
	v_add_u32_e32 v6, s9, v63
	v_lshl_or_b32 v40, v5, 10, v55
	v_mul_hi_i32 v5, v6, s33
	v_lshrrev_b32_e32 v7, 31, v5
	v_ashrrev_i32_e32 v5, 2, v5
	v_add_u32_e32 v5, v5, v7
	v_mad_u64_u32 v[6:7], s[6:7], v5, s74, v[6:7]
	v_lshl_or_b32 v7, v6, 7, v58
	v_min_i32_e32 v7, 0x8ff, v7
	v_cmp_lt_i32_e32 vcc, -1, v6
	v_mov_b32_e32 v39, v3
	v_lshl_or_b32 v4, v4, 10, v55
	v_cndmask_b32_e32 v6, 0, v7, vcc
	v_mad_u64_u32 v[6:7], s[6:7], v5, s75, v[6:7]
	v_add_u32_e32 v5, s8, v62
	v_min_i32_e32 v5, 31, v5
	v_lshl_or_b32 v42, v5, 10, v55
	v_mul_hi_i32 v5, v8, s33
	v_lshrrev_b32_e32 v7, 31, v5
	v_ashrrev_i32_e32 v5, 2, v5
	v_add_u32_e32 v5, v5, v7
	v_mad_u64_u32 v[8:9], s[6:7], v5, s74, v[8:9]
	v_lshl_or_b32 v7, v8, 7, v66
	v_min_i32_e32 v7, 0x8ff, v7
	v_cmp_lt_i32_e32 vcc, -1, v8
	v_lshl_add_u64 v[10:11], v[38:39], 1, s[18:19]
	v_mov_b32_e32 v41, v3
	v_cndmask_b32_e32 v8, 0, v7, vcc
	v_mad_u64_u32 v[8:9], s[6:7], v5, s75, v[8:9]
	v_add_u32_e32 v5, s8, v64
	v_readfirstlane_b32 s6, v56
	v_min_i32_e32 v5, 31, v5
	s_mov_b32 m0, s6
	v_readfirstlane_b32 s6, v67
	v_lshl_or_b32 v44, v5, 10, v55
	global_load_lds_dwordx4 v[46:47], off
	s_mov_b32 m0, s6
	v_mov_b32_e32 v5, v3
	v_readfirstlane_b32 s6, v68
	global_load_lds_dwordx4 v[10:11], off
	v_lshl_add_u64 v[48:49], v[4:5], 1, s[36:37]
	s_mov_b32 m0, s6
	v_readfirstlane_b32 s6, v69
	v_lshl_or_b32 v6, v6, 10, v55
	global_load_lds_dwordx4 v[48:49], off
	v_lshl_add_u64 v[4:5], v[40:41], 1, s[18:19]
	s_mov_b32 m0, s6
	v_mov_b32_e32 v7, v3
	v_readfirstlane_b32 s6, v70
	v_lshl_add_u64 v[50:51], v[6:7], 1, s[36:37]
	s_mov_b32 m0, s6
	v_mov_b32_e32 v43, v3
	v_readfirstlane_b32 s6, v71
	v_lshl_or_b32 v8, v8, 10, v55
	global_load_lds_dwordx4 v[50:51], off
	v_lshl_add_u64 v[4:5], v[42:43], 1, s[18:19]
	s_mov_b32 m0, s6
	v_mov_b32_e32 v9, v3
	v_readfirstlane_b32 s6, v72
	v_lshl_add_u64 v[52:53], v[8:9], 1, s[36:37]
	s_mov_b32 m0, s6
	v_mov_b32_e32 v45, v3
	v_readfirstlane_b32 s6, v73
	global_load_lds_dwordx4 v[52:53], off
	v_lshl_add_u64 v[4:5], v[44:45], 1, s[18:19]
	s_mov_b32 m0, s6
	v_readfirstlane_b32 s6, v74
	v_readfirstlane_b32 s6, v56
	s_add_i32 m0, s6, 0x10000
	v_lshl_add_u64 v[4:5], v[46:47], 0, s[22:23]
	global_load_lds_dwordx4 v[4:5], off
	v_or_b32_e32 v2, 64, v38
	s_add_i32 m0, s6, 0x18000
	v_lshl_add_u64 v[4:5], v[2:3], 1, s[18:19]
	global_load_lds_dwordx4 v[4:5], off
	s_add_i32 m0, s6, 0x12000
	v_lshl_add_u64 v[4:5], v[48:49], 0, s[22:23]
	global_load_lds_dwordx4 v[4:5], off
	s_add_i32 m0, s6, 0x14000
	v_lshl_add_u64 v[4:5], v[50:51], 0, s[22:23]
	global_load_lds_dwordx4 v[4:5], off
	s_add_i32 m0, s6, 0x16000
	v_lshl_add_u64 v[4:5], v[52:53], 0, s[22:23]
	global_load_lds_dwordx4 v[4:5], off
	s_waitcnt vmcnt(5)
	s_barrier
	v_readfirstlane_b32 s6, v56
	s_add_i32 m0, s6, 0x1a000
	v_lshl_add_u64 v[4:5], v[46:47], 0, s[24:25]
	global_load_lds_dwordx4 v[4:5], off
	v_or_b32_e32 v2, 0x80, v38
	s_add_i32 m0, s6, 0x22000
	v_lshl_add_u64 v[4:5], v[2:3], 1, s[18:19]
	global_load_lds_dwordx4 v[4:5], off
	s_add_i32 m0, s6, 0x1c000
	v_lshl_add_u64 v[4:5], v[48:49], 0, s[24:25]
	global_load_lds_dwordx4 v[4:5], off
	s_add_i32 m0, s6, 0x1e000
	v_lshl_add_u64 v[4:5], v[50:51], 0, s[24:25]
	global_load_lds_dwordx4 v[4:5], off
	s_add_i32 m0, s6, 0x20000
	v_lshl_add_u64 v[4:5], v[52:53], 0, s[24:25]
	global_load_lds_dwordx4 v[4:5], off
	v_mov_b32_e32 v2, v3
	v_mov_b32_e32 v4, v3
	v_mov_b32_e32 v5, v3
	v_mov_b64_e32 v[28:29], v[4:5]
	v_mov_b64_e32 v[24:25], v[4:5]
	v_mov_b64_e32 v[20:21], v[4:5]
	v_mov_b64_e32 v[16:17], v[4:5]
	v_mov_b64_e32 v[12:13], v[4:5]
	v_mov_b64_e32 v[8:9], v[4:5]
	v_mov_b64_e32 v[32:33], v[4:5]
	v_mov_b64_e32 v[36:37], v[4:5]
	v_mov_b64_e32 v[26:27], v[2:3]
	v_mov_b64_e32 v[22:23], v[2:3]
	v_mov_b64_e32 v[18:19], v[2:3]
	v_mov_b64_e32 v[14:15], v[2:3]
	v_mov_b64_e32 v[10:11], v[2:3]
	v_mov_b64_e32 v[6:7], v[2:3]
	v_mov_b64_e32 v[30:31], v[2:3]
	v_mov_b64_e32 v[34:35], v[2:3]
	s_and_saveexec_b64 s[6:7], s[4:5]
	s_cbranch_execz .LBB0_1527
	s_setprio 2
	ds_read_b128 v[4:7], v83 offset:32768
	ds_read_b128 v[8:11], v83 offset:34816
	ds_read_b128 v[12:15], v82
	ds_read_b128 v[16:19], v82 offset:2048
	ds_read_b128 v[28:31], v82 offset:4096
	ds_read_b128 v[32:35], v82 offset:6144
	ds_read_b128 v[102:105], v85 offset:32768
	s_waitcnt lgkmcnt(0)
	v_mfma_f32_16x16x32_bf16 v[20:23], v[4:7], v[12:15], 0
	v_mfma_f32_16x16x32_bf16 v[12:15], v[8:11], v[12:15], 0
	v_mfma_f32_16x16x32_bf16 v[24:27], v[4:7], v[16:19], 0
	v_mfma_f32_16x16x32_bf16 v[16:19], v[8:11], v[16:19], 0
	v_mfma_f32_16x16x32_bf16 v[98:101], v[8:11], v[28:31], 0
	v_mfma_f32_16x16x32_bf16 v[106:109], v[8:11], v[32:35], 0
	ds_read_b128 v[110:113], v85 offset:34816
	ds_read_b128 v[8:11], v84
	ds_read_b128 v[114:117], v84 offset:2048
	v_mfma_f32_16x16x32_bf16 v[94:97], v[4:7], v[28:31], 0
	v_mfma_f32_16x16x32_bf16 v[4:7], v[4:7], v[32:35], 0
	s_waitcnt lgkmcnt(0)
	v_mfma_f32_16x16x32_bf16 v[34:37], v[102:105], v[8:11], v[20:23]
	v_mfma_f32_16x16x32_bf16 v[30:33], v[110:113], v[8:11], v[12:15]
	v_mfma_f32_16x16x32_bf16 v[26:29], v[102:105], v[114:117], v[24:27]
	v_mfma_f32_16x16x32_bf16 v[22:25], v[110:113], v[114:117], v[16:19]
	ds_read_b128 v[8:11], v84 offset:4096
	ds_read_b128 v[114:117], v84 offset:6144
	s_waitcnt lgkmcnt(0)
	v_mfma_f32_16x16x32_bf16 v[18:21], v[102:105], v[8:11], v[94:97]
	v_mfma_f32_16x16x32_bf16 v[14:17], v[110:113], v[8:11], v[98:101]
	v_mfma_f32_16x16x32_bf16 v[10:13], v[102:105], v[114:117], v[4:7]
	v_mfma_f32_16x16x32_bf16 v[6:9], v[110:113], v[114:117], v[106:109]

; __device__ __forceinline__ int get_tid512() { int t = threadIdx.x; asm volatile("" : "+v"(t)); return t; }
; __device__ __forceinline__ unsigned pack2(float a, float b) { unsigned r; asm("v_cvt_pk_bf16_f32 %0, %1, %2" : "=v"(r) : "v"(a), "v"(b)); return r; }
;   __device__ __forceinline__ float c4(int g, int rig, int col, f32x4 v) const {
;     const size_t row = (size_t)g * ostride + rig;
;     if (kpe && col >= ropecol) {
;       const int i0 = col - ropecol;
;       f32x4 o = v;
;       const float p0 = __shfl_xor(v[0], 32), p1 = __shfl_xor(v[1], 32), p2 = __shfl_xor(v[2], 32), p3 = __shfl_xor(v[3], 32);
;       const float pv[4] = {p0, p1, p2, p3};
;       if (rig >= 256) {
;         const int t = rig - 256;
;         const int quarter = i0 >> 3;
;         const float pos = (quarter < 2) ? (float)(t >> 6) : (float)(t & 63);
; #pragma unroll
;         for (int j = 0; j < 4; ++j) {
;           const int idx = (i0 & 7) + j;
;           const float inv = exp2f(-(float)idx * (13.287712379549449f / 8.0f));
;           const float ang = pos * inv;
;           const float cs = __cosf(ang), sn = __sinf(ang);
;           o[j] = v[j] * cs + ((quarter & 1) ? pv[j] : -pv[j]) * sn;
;         }
;       }
;       uint2 u; u.x = pack2(o[0], o[1]); u.y = pack2(o[2], o[3]);
;       *(uint2*)(kpe + row * 32 + i0) = u;
; template <bool SWAP, class Epi, bool THIN = false> ...
;     ...
;     __syncthreads();
;     const int te = get_tid512();
;     const int fr_e = te & 15, fq_e = (te & 63) >> 4, wr_e = te >> 7, wc_e = (te >> 6) & 1;
;     const int sub = 2 * mt + (wr_e >> 1);
;     const int g = sub / tpg, ti = sub - g * tpg;
;     const int rig0 = ti * step - halo;
;     const int rw = (wr_e & 1) * 64;
;     if constexpr (Epi::KIND == 0) {
; #pragma unroll
;       for (int m = 0; m < 4; ++m) {
;         const int rig = rig0 + rw + m * 16 + fr_e;
;         if constexpr (Epi::ROWSUM) {
;           float ss = 0.f;
; #pragma unroll
;           for (int n = 0; n < 8; ++n) {
;             const int col = nt * 256 + wc_e * 128 + n * 16 + fq_e * 4;
;             if (col < N) ss += epi.c4(g, rig, col, acc[m][n]);
;           }
;           ss += __shfl_xor(ss, 16); ss += __shfl_xor(ss, 32);
;           if (fq_e == 0) epi.rowsum(g, rig, nt * 2 + wc_e, ss);
.LBB0_1557:
	s_or_b64 exec, exec, s[6:7]
	s_setprio 0
	v_bfe_u32 v38, v1, 6, 2
	v_lshrrev_b32_e32 v39, 8, v1
	v_lshl_or_b32 v38, v38, 1, v39
	v_and_b32_e32 v40, 63, v1
	v_lshl_or_b32 v40, v38, 6, v40
	s_waitcnt vmcnt(0) lgkmcnt(0)
	s_barrier
	s_nop 0
	v_ashrrev_i32_e32 v2, 8, v40
	v_add_u32_e32 v2, s9, v2
	v_mul_hi_i32 v38, v2, s33
	v_lshrrev_b32_e32 v39, 31, v38
	v_ashrrev_i32_e32 v38, 2, v38
	v_add_u32_e32 v48, v38, v39
	v_mad_u64_u32 v[38:39], s[6:7], v48, s74, v[2:3]
	v_lshrrev_b32_e32 v2, 1, v40
	v_bfe_u32 v49, v40, 4, 2
	v_bfe_u32 v5, v40, 6, 1
	v_and_b32_e32 v2, 64, v2
	v_and_b32_e32 v4, 15, v40
	v_lshl_or_b32 v42, v38, 7, v2
	v_lshlrev_b32_e32 v2, 7, v5
	v_lshlrev_b32_e32 v50, 2, v49
	v_or3_b32 v2, v2, v50, s8
	v_add_u32_e32 v38, 0xffffff00, v42
	v_or_b32_e32 v44, v42, v4
	v_lshrrev_b32_e32 v51, 6, v38
	v_ashrrev_i32_e32 v45, 31, v44
	v_cmp_lt_i32_e64 s[6:7], s78, v44
	v_cmp_gt_i32_e64 s[8:9], 32, v2
	v_mov_b32_e32 v40, 0
	s_and_saveexec_b64 s[12:13], s[8:9]
	s_cbranch_execz .LBB0_1564
	v_mad_i64_i32 v[46:47], s[10:11], v48, s75, v[44:45]
	s_cmp_lt_i32 s46, 0
	s_cselect_b64 s[10:11], -1, 0
	s_or_b64 s[14:15], s[20:21], s[10:11]
	s_mov_b64 s[10:11], -1
	s_and_b64 vcc, exec, s[14:15]
	s_cbranch_vccnz .LBB0_1562
	v_and_b32_e32 v39, 64, v90
	v_xor_b32_e32 v38, 32, v90
	v_add_u32_e32 v39, 64, v39
	v_cmp_lt_i32_e32 vcc, v38, v39
	s_nop 1
	v_cndmask_b32_e32 v38, v90, v38, vcc
	v_lshlrev_b32_e32 v38, 2, v38
	ds_bpermute_b32 v53, v38, v34
	ds_bpermute_b32 v93, v38, v35
	ds_bpermute_b32 v52, v38, v36
	ds_bpermute_b32 v43, v38, v37
	v_mov_b64_e32 v[40:41], v[36:37]
	v_mov_b64_e32 v[38:39], v[34:35]
	s_and_saveexec_b64 s[14:15], s[6:7]
	s_cbranch_execz .LBB0_1561
	v_and_b32_e32 v96, 4, v50
	v_cvt_f32_ubyte0_e32 v39, v96
	v_cmp_gt_u32_e32 vcc, 16, v2
	v_mul_f32_e32 v40, 0xbfd49a78, v39
	s_nop 0
	v_cndmask_b32_e32 v38, v4, v51, vcc
	v_cmp_gt_f32_e32 vcc, s79, v40
	v_cvt_f32_u32_e32 v97, v38
	s_nop 0
	v_cndmask_b32_e32 v40, 0, v91, vcc
	v_fmac_f32_e32 v40, 0xbfd49a78, v39
	v_exp_f32_e32 v39, v40
	v_cndmask_b32_e32 v38, 0, v92, vcc
	v_ldexp_f32 v38, v39, v38
	v_mul_f32_e32 v38, v38, v97
	v_mul_f32_e32 v39, 0.15915494, v38
	v_or_b32_e32 v38, 1, v96
	v_cvt_f32_ubyte0_e32 v38, v38
	v_mul_f32_e32 v40, 0xbfd49a78, v38
	v_cmp_gt_f32_e32 vcc, s79, v40
	s_nop 1
	v_cndmask_b32_e32 v40, 0, v91, vcc
	v_fmac_f32_e32 v40, 0xbfd49a78, v38
	v_exp_f32_e32 v41, v40
	v_cos_f32_e32 v38, v39
	v_sin_f32_e32 v40, v39
	v_cndmask_b32_e32 v39, 0, v92, vcc
	v_cmp_gt_u32_e32 vcc, 2, v49
	v_ldexp_f32 v39, v41, v39
	v_mul_f32_e32 v39, v39, v97
	s_waitcnt lgkmcnt(2)
	v_cndmask_b32_e64 v95, v93, -v93, vcc
	v_or_b32_e32 v93, 2, v96
	v_cvt_f32_ubyte0_e32 v93, v93
	v_mul_f32_e32 v94, 0xbfd49a78, v93
	v_mul_f32_e32 v41, 0.15915494, v39
	v_cmp_gt_f32_e64 s[10:11], s79, v94
	v_cos_f32_e32 v39, v41
	v_sin_f32_e32 v41, v41
	v_cndmask_b32_e64 v94, 0, v91, s[10:11]
	v_fmac_f32_e32 v94, 0xbfd49a78, v93
	v_exp_f32_e32 v93, v94
	v_cndmask_b32_e64 v94, v53, -v53, vcc
	v_pk_mul_f32 v[40:41], v[40:41], v[94:95]
	v_or_b32_e32 v94, 3, v96
	v_cndmask_b32_e64 v53, 0, v92, s[10:11]
	v_cvt_f32_ubyte0_e32 v94, v94
	v_ldexp_f32 v53, v93, v53
	v_mul_f32_e32 v95, 0xbfd49a78, v94
	v_mul_f32_e32 v53, v53, v97
	v_cmp_gt_f32_e64 s[10:11], s79, v95
	v_mul_f32_e32 v53, 0.15915494, v53
	v_cos_f32_e32 v93, v53
	v_cndmask_b32_e64 v95, 0, v91, s[10:11]
	v_fmac_f32_e32 v95, 0xbfd49a78, v94
	v_exp_f32_e32 v95, v95
	v_mul_f32_e32 v94, v36, v93
	s_waitcnt lgkmcnt(1)
	v_cndmask_b32_e64 v93, v52, -v52, vcc
	v_cndmask_b32_e64 v52, 0, v92, s[10:11]
	v_ldexp_f32 v52, v95, v52
	v_mul_f32_e32 v52, v52, v97
	v_sin_f32_e32 v53, v53
	v_mul_f32_e32 v95, 0.15915494, v52
	v_cos_f32_e32 v52, v95
	v_sin_f32_e32 v97, v95
	v_mul_f32_e32 v98, v53, v93
	s_waitcnt lgkmcnt(0)
	v_cndmask_b32_e64 v53, v43, -v43, vcc
	v_mov_b32_e32 v96, v37
	v_pk_mul_f32 v[52:53], v[96:97], v[52:53]
	v_pk_fma_f32 v[38:39], v[34:35], v[38:39], v[40:41]
	v_mov_b32_e32 v95, v52
	v_mov_b32_e32 v99, v53
	v_pk_add_f32 v[40:41], v[94:95], v[98:99]
